# + closed-form unit scheduler in P2/P4/P8 when the grid is 256 workgroups (generic scheduler with two integer divisions bypassed)
# speedup vs baseline: 1.0011x; 1.0006x over previous
;     __device__ bool next(int i, Unit& u) const { if (i > 1 || !so.next(0, u)) return false; if (i == 1) { u.pm += 64; u.pn += 4; } return true; }
;     __host__ __device__ bool next(int i, Unit& u) const {
;         const long L = (long)i * G + c; if (L >= nwg) return false;
;         int wgid = (int)L; { const int q = nwg / NXCD, r = nwg % NXCD, xcd = wgid % NXCD, off = wgid / NXCD; wgid = (xcd < r ? xcd * (q + 1) : r * (q + 1) + (xcd - r) * q) + off; }
;         const int nig = WGM * nN, gid = wgid / nig, fm = gid * WGM, gsz = (nM - fm) < WGM ? (nM - fm) : WGM;
;         u.pm = fm + ((wgid % nig) % gsz); u.pn = (wgid % nig) / gsz; return true;
;     }
.LBB0_191:
	s_add_i32 s59, s59, 1
	s_mul_i32 s4, s59, s64
	s_mul_hi_u32 s5, s59, s65
	s_add_i32 s5, s5, s4
	s_mul_i32 s4, s59, s65
	s_add_u32 s20, s4, s2
	s_addc_u32 s21, s5, s54
	v_cmp_gt_i64_e32 vcc, s[20:21], v[142:143]
	v_cmp_lt_i64_e64 s[4:5], s[20:21], v[140:141]
	s_cbranch_vccnz .LBB0_193
	s_cmp_lg_u32 s65, 0x100
	s_cbranch_scc1 .Lp2_sched_orig
	s_lshr_b32 s16, s2, 6
	s_lshl2_add_u32 s16, s59, s16
	s_and_b32 s18, s2, 7
	s_lshl_b32 s18, s18, 3
	s_bfe_u32 s17, s2, 0x30003
	s_add_i32 s18, s18, s17
	s_branch .LBB0_193
.Lp2_sched_orig:
	s_ashr_i32 s16, s20, 31
	s_lshr_b32 s16, s16, 29
	s_add_i32 s16, s20, s16
	s_ashr_i32 s17, s16, 3
	s_and_b32 s16, s16, -8
	s_sub_i32 s16, s20, s16
	s_cmp_lt_i32 s16, 0
	s_cselect_b32 s18, s55, 0xb0
	s_mul_i32 s16, s16, s18
	s_add_i32 s16, s16, s17
	s_mul_hi_i32 s17, s16, 0x2e8ba2e9
	s_lshr_b32 s18, s17, 31
	s_ashr_i32 s17, s17, 5
	s_add_i32 s17, s17, s18
	s_lshl_b32 s18, s17, 3
	s_sub_i32 s19, 64, s18
	s_min_i32 s19, s19, 8
	s_abs_i32 s20, s19
	v_cvt_f32_u32_e32 v0, s20
	s_sub_i32 s34, 0, s20
	s_mulk_i32 s17, 0xb0
	s_sub_i32 s17, s16, s17
	v_rcp_iflag_f32_e32 v0, v0
	s_abs_i32 s16, s17
	s_xor_b32 s21, s17, s19
	s_ashr_i32 s21, s21, 31
	v_mul_f32_e32 v0, 0x4f7ffffe, v0
	v_cvt_u32_f32_e32 v0, v0
	s_nop 0
	v_readfirstlane_b32 s35, v0
	s_mul_i32 s34, s34, s35
	s_mul_hi_u32 s34, s35, s34
	s_add_i32 s35, s35, s34
	s_mul_hi_u32 s34, s16, s35
	s_mul_i32 s35, s34, s20
	s_sub_i32 s16, s16, s35
	s_add_i32 s52, s34, 1
	s_sub_i32 s35, s16, s20
	s_cmp_ge_u32 s16, s20
	s_cselect_b32 s34, s52, s34
	s_cselect_b32 s16, s35, s16
	s_add_i32 s35, s34, 1
	s_cmp_ge_u32 s16, s20
	s_cselect_b32 s16, s35, s34
	s_xor_b32 s16, s16, s21
	s_sub_i32 s16, s16, s21
	s_mul_i32 s19, s16, s19
	s_sub_i32 s17, s17, s19
	s_add_i32 s18, s18, s17

;     __device__ bool next(int i, Unit& u) const { if (i > 1 || !so.next(0, u)) return false; if (i == 1) { u.pm += 64; u.pn += 4; } return true; }
;     __host__ __device__ bool next(int i, Unit& u) const {
;         const long L = (long)i * G + c; if (L >= nwg) return false;
;         int wgid = (int)L; { const int q = nwg / NXCD, r = nwg % NXCD, xcd = wgid % NXCD, off = wgid / NXCD; wgid = (xcd < r ? xcd * (q + 1) : r * (q + 1) + (xcd - r) * q) + off; }
;         const int nig = WGM * nN, gid = wgid / nig, fm = gid * WGM, gsz = (nM - fm) < WGM ? (nM - fm) : WGM;
;         u.pm = fm + ((wgid % nig) % gsz); u.pn = (wgid % nig) / gsz; return true;
;     }
.LBB0_400:
	s_add_i32 s78, s78, 1
	s_mul_i32 s4, s78, s72
	s_mul_hi_u32 s5, s78, s73
	s_add_i32 s5, s5, s4
	s_mul_i32 s4, s78, s73
	s_add_u32 s44, s4, s2
	s_addc_u32 s45, s5, s3
	v_cmp_gt_i64_e32 vcc, s[44:45], v[182:183]
	v_cmp_lt_i64_e64 s[4:5], s[44:45], v[180:181]
	s_cbranch_vccnz .LBB0_406
	s_cmp_lg_u32 s73, 0x100
	s_cbranch_scc1 .Lp4_sched_orig
	s_lshr_b32 s22, s2, 6
	s_lshl2_add_u32 s22, s78, s22
	s_and_b32 s40, s2, 7
	s_lshl_b32 s40, s40, 3
	s_bfe_u32 s7, s2, 0x30003
	s_add_i32 s40, s40, s7
	s_branch .LBB0_406
.Lp4_sched_orig:
	s_ashr_i32 s7, s44, 31
	s_lshr_b32 s7, s7, 29
	s_add_i32 s7, s44, s7
	s_and_b32 s9, s7, -8
	s_sub_i32 s9, s44, s9
	s_cmp_gt_i32 s9, -1
	s_mov_b64 s[22:23], -1
	s_cbranch_scc0 .LBB0_403
	s_lshl_b32 s12, s9, 7
	s_mov_b64 s[22:23], 0

;     __device__ bool next(int i, Unit& u) const { if (i > 1 || !so.next(0, u)) return false; if (i == 1) { u.pm += 64; u.pn += 4; } return true; }
;     __host__ __device__ bool next(int i, Unit& u) const {
;         const long L = (long)i * G + c; if (L >= nwg) return false;
;         int wgid = (int)L; { const int q = nwg / NXCD, r = nwg % NXCD, xcd = wgid % NXCD, off = wgid / NXCD; wgid = (xcd < r ? xcd * (q + 1) : r * (q + 1) + (xcd - r) * q) + off; }
;         const int nig = WGM * nN, gid = wgid / nig, fm = gid * WGM, gsz = (nM - fm) < WGM ? (nM - fm) : WGM;
;         u.pm = fm + ((wgid % nig) % gsz); u.pn = (wgid % nig) / gsz; return true;
;     }
.LBB0_904:
	s_add_i32 s47, s47, 1
	s_mul_i32 s4, s47, s50
	s_mul_hi_u32 s5, s47, s51
	s_add_i32 s5, s5, s4
	s_mul_i32 s4, s47, s51
	s_add_u32 s28, s4, s2
	s_addc_u32 s29, s5, s3
	v_cmp_gt_i64_e32 vcc, s[28:29], v[160:161]
	v_cmp_lt_i64_e64 s[4:5], s[28:29], v[158:159]
	s_cbranch_vccnz .LBB0_906
	s_cmp_lg_u32 s51, 0x100
	s_cbranch_scc1 .Lp8_sched_orig
	s_lshr_b32 s20, s2, 6
	s_lshl2_add_u32 s20, s47, s20
	s_and_b32 s22, s2, 7
	s_lshl_b32 s22, s22, 3
	s_bfe_u32 s21, s2, 0x30003
	s_add_i32 s22, s22, s21
	s_branch .LBB0_906
.Lp8_sched_orig:
	s_ashr_i32 s20, s28, 31
	s_lshr_b32 s20, s20, 29
	s_add_i32 s20, s28, s20
	s_ashr_i32 s21, s20, 3
	s_and_b32 s20, s20, -8
	s_sub_i32 s20, s28, s20
	s_cmp_lt_i32 s20, 0
	s_cselect_b32 s22, s41, 0xb0
	s_mul_i32 s20, s20, s22
	s_add_i32 s20, s20, s21
	s_mul_hi_i32 s21, s20, 0x2e8ba2e9
	s_lshr_b32 s22, s21, 31
	s_ashr_i32 s21, s21, 5
	s_add_i32 s21, s21, s22
	s_lshl_b32 s22, s21, 3
	s_sub_i32 s23, 64, s22
	s_min_i32 s23, s23, 8
	s_abs_i32 s28, s23
	v_cvt_f32_u32_e32 v2, s28
	s_sub_i32 s38, 0, s28
	s_mulk_i32 s21, 0xb0
	s_sub_i32 s21, s20, s21
	v_rcp_iflag_f32_e32 v2, v2
	s_abs_i32 s20, s21
	s_xor_b32 s29, s21, s23
	s_ashr_i32 s29, s29, 31
	v_mul_f32_e32 v2, 0x4f7ffffe, v2
	v_cvt_u32_f32_e32 v2, v2
	s_nop 0
	v_readfirstlane_b32 s39, v2
	s_mul_i32 s38, s38, s39
	s_mul_hi_u32 s38, s39, s38
	s_add_i32 s39, s39, s38
	s_mul_hi_u32 s38, s20, s39
	s_mul_i32 s39, s38, s28
	s_sub_i32 s20, s20, s39
	s_add_i32 s58, s38, 1
	s_sub_i32 s39, s20, s28
	s_cmp_ge_u32 s20, s28
	s_cselect_b32 s38, s58, s38
	s_cselect_b32 s20, s39, s20
	s_add_i32 s39, s38, 1
	s_cmp_ge_u32 s20, s28
	s_cselect_b32 s20, s39, s38
	s_xor_b32 s20, s20, s29
	s_sub_i32 s20, s20, s29
	s_mul_i32 s23, s20, s23
	s_sub_i32 s21, s21, s23
	s_add_i32 s22, s22, s21
